# P4 epilogue: residual loads issued four row groups ahead (four 16-register sets in v184..v247, counted waits) instead of 16 serial load-pair/wait rounds
# baseline (speedup 1.0000x reference)
; __device__ __forceinline__ unsigned cvt_pk_bf16(float lo, float hi) { f32x2v_t v = {lo, hi}; bf16x2v_t b = __builtin_convertvector(v, bf16x2v_t); return __builtin_bit_cast(unsigned, b); }
;     __device__ __forceinline__ void operator()(PG8_ACC, const Unit& u, int wr, int wc, int fr, int fq) const {
;     ...
;         for (int ai = 0; ai < 2; ++ai)
; #pragma unroll
;             for (int m = 0; m < 4; ++m) { const int row = row0 + ai * HALF + m * 16; const size_t off = (size_t)row * ld + col0; float s = 0.f;
; #pragma unroll
;                 for (int bj = 0; bj < 2; ++bj) {
;                     const f32x4 r0 = *(const f32x4*)(res + off + bj * HALF), r1 = *(const f32x4*)(res + off + bj * HALF + 4);
;                     const f32x4 v0 = acc[ai][bj][m][0] + r0, v1 = acc[ai][bj][m][1] + r1;
;                     *(f32x4*)(out + off + bj * HALF) = v0; *(f32x4*)(out + off + bj * HALF + 4) = v1;
;                     s += (v0[0] * v0[0] + v0[1] * v0[1]) + (v0[2] * v0[2] + v0[3] * v0[3]) + (v1[0] * v1[0] + v1[1] * v1[1]) + (v1[2] * v1[2] + v1[3] * v1[3]);
;                     const f32x4 h0 = v0 * gv[bj][0], h1 = v1 * gv[bj][1];
;                     u32x4 w; w.x = cvt_pk_bf16(h0[0], h0[1]); w.y = cvt_pk_bf16(h0[2], h0[3]); w.z = cvt_pk_bf16(h1[0], h1[1]); w.w = cvt_pk_bf16(h1[2], h1[3]);
;                     *(u32x4*)(H + (size_t)row * ldh + col0 + bj * HALF) = w; }
;                 s += shx<16>(s); s = sum_halves(s);
;                 if (fq == 0) atomicAdd(SSQ + row, s); }
.LBB0_636:
	v_lshl_add_u32 v162, s68, 8, v164
	v_lshl_or_b32 v160, s50, 8, v166
	v_ashrrev_i32_e32 v163, 31, v162
	v_ashrrev_i32_e32 v161, 31, v160
	v_lshlrev_b64 v[80:81], 10, v[162:163]
	v_lshl_add_u64 v[80:81], v[80:81], 0, v[160:161]
	v_lshlrev_b64 v[178:179], 2, v[80:81]
	v_lshl_add_u64 v[180:181], s[16:17], 0, v[178:179]
	v_mov_b64_e32 v[248:249], v[180:181]
	s_mov_b64 s[100:101], 0x10000
	global_load_dwordx4 v[184:187], v[248:249], off
	global_load_dwordx4 v[188:191], v[248:249], off offset:16
	global_load_dwordx4 v[192:195], v[248:249], off offset:512
	global_load_dwordx4 v[196:199], v[248:249], off offset:528
	v_lshl_add_u64 v[248:249], v[248:249], 0, s[100:101]
	global_load_dwordx4 v[200:203], v[248:249], off
	global_load_dwordx4 v[204:207], v[248:249], off offset:16
	global_load_dwordx4 v[208:211], v[248:249], off offset:512
	global_load_dwordx4 v[212:215], v[248:249], off offset:528
	v_lshl_add_u64 v[248:249], v[248:249], 0, s[100:101]
	global_load_dwordx4 v[216:219], v[248:249], off
	global_load_dwordx4 v[220:223], v[248:249], off offset:16
	global_load_dwordx4 v[224:227], v[248:249], off offset:512
	global_load_dwordx4 v[228:231], v[248:249], off offset:528
	v_lshl_add_u64 v[248:249], v[248:249], 0, s[100:101]
	global_load_dwordx4 v[232:235], v[248:249], off
	global_load_dwordx4 v[236:239], v[248:249], off offset:16
	global_load_dwordx4 v[240:243], v[248:249], off offset:512
	global_load_dwordx4 v[244:247], v[248:249], off offset:528
	v_lshl_add_u64 v[248:249], v[248:249], 0, s[100:101]
	v_lshl_add_u64 v[84:85], v[160:161], 2, s[22:23]
	global_load_dwordx4 v[92:95], v[84:85], off
	global_load_dwordx4 v[88:91], v[84:85], off offset:16
	v_mov_b64_e32 v[80:81], s[18:19]
	v_mad_i64_i32 v[80:81], s[8:9], v162, s66, v[80:81]
	v_lshl_add_u64 v[182:183], v[160:161], 1, v[80:81]
	v_lshl_add_u64 v[178:179], s[12:13], 0, v[178:179]
	global_load_dwordx4 v[80:83], v[84:85], off offset:528
	s_nop 0
	global_load_dwordx4 v[84:87], v[84:85], off offset:512
	s_waitcnt vmcnt(0)
	v_pk_add_f32 v[142:143], v[142:143], v[186:187]
	v_pk_add_f32 v[140:141], v[140:141], v[184:185]
	v_pk_add_f32 v[138:139], v[138:139], v[190:191]
	v_pk_add_f32 v[136:137], v[136:137], v[188:189]
	v_pk_mul_f32 v[172:173], v[94:95], v[142:143]
	v_pk_mul_f32 v[170:171], v[92:93], v[140:141]
	v_pk_mul_f32 v[174:175], v[90:91], v[138:139]
	v_pk_mul_f32 v[176:177], v[88:89], v[136:137]
	v_cvt_pk_bf16_f32 v170, v170, v171
	v_cvt_pk_bf16_f32 v171, v172, v173
	v_cvt_pk_bf16_f32 v172, v176, v177
	v_cvt_pk_bf16_f32 v173, v174, v175
	global_store_dwordx4 v[178:179], v[140:143], off
	global_store_dwordx4 v[178:179], v[136:139], off offset:16
	global_store_dwordx4 v[182:183], v[170:173], off
	v_mul_f32_e32 v141, v141, v141
	v_mul_f32_e32 v143, v143, v143
	v_mul_f32_e32 v137, v137, v137
	v_fmac_f32_e32 v141, v140, v140
	v_fmac_f32_e32 v143, v142, v142
	v_mul_f32_e32 v139, v139, v139
	v_fmac_f32_e32 v137, v136, v136
	v_add_f32_e32 v136, v141, v143
	v_fmac_f32_e32 v139, v138, v138
	v_add_f32_e32 v136, v136, v137
	v_add_f32_e32 v180, v139, v136
	v_pk_add_f32 v[134:135], v[134:135], v[194:195]
	v_pk_add_f32 v[132:133], v[132:133], v[192:193]
	v_pk_add_f32 v[128:129], v[128:129], v[196:197]
	v_mul_f32_e32 v170, v133, v133
	v_mul_f32_e32 v171, v135, v135
	v_pk_add_f32 v[130:131], v[130:131], v[198:199]
	v_mul_f32_e32 v172, v129, v129
	v_fmac_f32_e32 v170, v132, v132
	v_fmac_f32_e32 v171, v134, v134
	global_store_dwordx4 v[178:179], v[132:135], off offset:512
	global_store_dwordx4 v[178:179], v[128:131], off offset:528
	v_mul_f32_e32 v173, v131, v131
	v_pk_mul_f32 v[142:143], v[80:81], v[128:129]
	v_fmac_f32_e32 v172, v128, v128
	v_add_f32_e32 v129, v170, v171
	v_fmac_f32_e32 v173, v130, v130
	v_add_f32_e32 v129, v129, v172
	v_add_f32_e32 v129, v173, v129
	v_pk_mul_f32 v[138:139], v[84:85], v[132:133]
	v_add_f32_e32 v132, v180, v129
	ds_swizzle_b32 v133, v132 offset:swizzle(SWAP,16)
	v_pk_mul_f32 v[136:137], v[86:87], v[134:135]
	v_pk_mul_f32 v[140:141], v[82:83], v[130:131]
	v_cvt_pk_bf16_f32 v128, v138, v139
	v_cvt_pk_bf16_f32 v129, v136, v137
	v_cvt_pk_bf16_f32 v130, v142, v143
	v_cvt_pk_bf16_f32 v131, v140, v141
	global_store_dwordx4 v[182:183], v[128:131], off offset:256
	s_waitcnt lgkmcnt(0)
	s_nop 0
	v_add_f32_e32 v128, v132, v133
	v_mov_b32_e32 v129, v128
	s_nop 1
	v_permlane32_swap_b32_e32 v128, v129
	s_and_saveexec_b64 s[8:9], s[4:5]
	s_cbranch_execz .LBB0_638
	v_lshl_add_u64 v[130:131], v[162:163], 2, s[28:29]
	v_add_f32_e32 v128, v128, v129
	global_atomic_add_f32 v[130:131], v128, off
; __device__ __forceinline__ unsigned cvt_pk_bf16(float lo, float hi) { f32x2v_t v = {lo, hi}; bf16x2v_t b = __builtin_convertvector(v, bf16x2v_t); return __builtin_bit_cast(unsigned, b); }
;     __device__ __forceinline__ void operator()(PG8_ACC, const Unit& u, int wr, int wc, int fr, int fq) const {
;     ...
;         for (int ai = 0; ai < 2; ++ai)
; #pragma unroll
;             for (int m = 0; m < 4; ++m) { const int row = row0 + ai * HALF + m * 16; const size_t off = (size_t)row * ld + col0; float s = 0.f;
; #pragma unroll
;                 for (int bj = 0; bj < 2; ++bj) {
;                     const f32x4 r0 = *(const f32x4*)(res + off + bj * HALF), r1 = *(const f32x4*)(res + off + bj * HALF + 4);
;                     const f32x4 v0 = acc[ai][bj][m][0] + r0, v1 = acc[ai][bj][m][1] + r1;
;                     *(f32x4*)(out + off + bj * HALF) = v0; *(f32x4*)(out + off + bj * HALF + 4) = v1;
;                     s += (v0[0] * v0[0] + v0[1] * v0[1]) + (v0[2] * v0[2] + v0[3] * v0[3]) + (v1[0] * v1[0] + v1[1] * v1[1]) + (v1[2] * v1[2] + v1[3] * v1[3]);
;                     const f32x4 h0 = v0 * gv[bj][0], h1 = v1 * gv[bj][1];
;                     u32x4 w; w.x = cvt_pk_bf16(h0[0], h0[1]); w.y = cvt_pk_bf16(h0[2], h0[3]); w.z = cvt_pk_bf16(h1[0], h1[1]); w.w = cvt_pk_bf16(h1[2], h1[3]);
;                     *(u32x4*)(H + (size_t)row * ldh + col0 + bj * HALF) = w; }
;                 s += shx<16>(s); s = sum_halves(s);
;                 if (fq == 0) atomicAdd(SSQ + row, s); }
.LBB0_638:
	s_or_b64 exec, exec, s[8:9]
	s_mov_b64 s[98:99], 0x40000
	v_lshl_add_u64 v[248:249], v[248:249], 0, s[98:99]
	global_load_dwordx4 v[184:187], v[248:249], off
	global_load_dwordx4 v[188:191], v[248:249], off offset:16
	global_load_dwordx4 v[192:195], v[248:249], off offset:512
	global_load_dwordx4 v[196:199], v[248:249], off offset:528
	v_lshl_add_u64 v[248:249], v[248:249], 0, s[100:101]
	v_or_b32_e32 v128, 16, v162
	v_ashrrev_i32_e32 v129, 31, v128
	v_lshlrev_b64 v[130:131], 10, v[128:129]
	v_lshl_add_u64 v[130:131], v[130:131], 0, v[160:161]
	v_lshlrev_b64 v[138:139], 2, v[130:131]
	v_lshl_add_u64 v[140:141], s[16:17], 0, v[138:139]
	v_mov_b64_e32 v[142:143], s[18:19]
	v_mad_i64_i32 v[142:143], s[8:9], v128, s66, v[142:143]
	v_lshl_add_u64 v[142:143], v[160:161], 1, v[142:143]
	v_lshl_add_u64 v[138:139], s[12:13], 0, v[138:139]
	v_pk_add_f32 v[126:127], v[126:127], v[202:203]
	v_pk_add_f32 v[124:125], v[124:125], v[200:201]
	v_pk_add_f32 v[122:123], v[122:123], v[206:207]
	v_pk_add_f32 v[120:121], v[120:121], v[204:205]
	v_pk_mul_f32 v[132:133], v[94:95], v[126:127]
	v_pk_mul_f32 v[130:131], v[92:93], v[124:125]
	v_pk_mul_f32 v[134:135], v[90:91], v[122:123]
	v_pk_mul_f32 v[136:137], v[88:89], v[120:121]
	v_cvt_pk_bf16_f32 v130, v130, v131
	v_cvt_pk_bf16_f32 v131, v132, v133
	v_cvt_pk_bf16_f32 v132, v136, v137
	v_cvt_pk_bf16_f32 v133, v134, v135
	global_store_dwordx4 v[138:139], v[124:127], off
	global_store_dwordx4 v[138:139], v[120:123], off offset:16
	global_store_dwordx4 v[142:143], v[130:133], off
	v_mul_f32_e32 v125, v125, v125
	v_mul_f32_e32 v127, v127, v127
	v_mul_f32_e32 v121, v121, v121
	v_fmac_f32_e32 v125, v124, v124
	v_fmac_f32_e32 v127, v126, v126
	v_mul_f32_e32 v123, v123, v123
	v_fmac_f32_e32 v121, v120, v120
	v_add_f32_e32 v120, v125, v127
	v_fmac_f32_e32 v123, v122, v122
	v_add_f32_e32 v120, v120, v121
	v_add_f32_e32 v140, v123, v120
	v_pk_add_f32 v[118:119], v[118:119], v[210:211]
	v_pk_add_f32 v[116:117], v[116:117], v[208:209]
	v_pk_add_f32 v[112:113], v[112:113], v[212:213]
	v_mul_f32_e32 v130, v117, v117
	v_mul_f32_e32 v131, v119, v119
	v_pk_add_f32 v[114:115], v[114:115], v[214:215]
	v_mul_f32_e32 v132, v113, v113
	v_fmac_f32_e32 v130, v116, v116
	v_fmac_f32_e32 v131, v118, v118
	global_store_dwordx4 v[138:139], v[116:119], off offset:512
	global_store_dwordx4 v[138:139], v[112:115], off offset:528
	v_mul_f32_e32 v133, v115, v115
	v_pk_mul_f32 v[126:127], v[80:81], v[112:113]
	v_fmac_f32_e32 v132, v112, v112
	v_add_f32_e32 v113, v130, v131
	v_fmac_f32_e32 v133, v114, v114
	v_add_f32_e32 v113, v113, v132
	v_add_f32_e32 v113, v133, v113
	v_pk_mul_f32 v[122:123], v[84:85], v[116:117]
	v_add_f32_e32 v116, v140, v113
	ds_swizzle_b32 v117, v116 offset:swizzle(SWAP,16)
	v_pk_mul_f32 v[120:121], v[86:87], v[118:119]
	v_pk_mul_f32 v[124:125], v[82:83], v[114:115]
	v_cvt_pk_bf16_f32 v112, v122, v123
	v_cvt_pk_bf16_f32 v113, v120, v121
	v_cvt_pk_bf16_f32 v114, v126, v127
	v_cvt_pk_bf16_f32 v115, v124, v125
	global_store_dwordx4 v[142:143], v[112:115], off offset:256
	s_waitcnt lgkmcnt(0)
	s_nop 0
	v_add_f32_e32 v112, v116, v117
	v_mov_b32_e32 v113, v112
	s_nop 1
	v_permlane32_swap_b32_e32 v112, v113
	s_and_saveexec_b64 s[8:9], s[4:5]
	s_cbranch_execz .LBB0_640
	v_lshl_add_u64 v[114:115], v[128:129], 2, s[28:29]
	v_add_f32_e32 v112, v112, v113
	global_atomic_add_f32 v[114:115], v112, off
.LBB0_640:
	s_or_b64 exec, exec, s[8:9]
	global_load_dwordx4 v[200:203], v[248:249], off
	global_load_dwordx4 v[204:207], v[248:249], off offset:16
	global_load_dwordx4 v[208:211], v[248:249], off offset:512
	global_load_dwordx4 v[212:215], v[248:249], off offset:528
	v_lshl_add_u64 v[248:249], v[248:249], 0, s[100:101]
	v_or_b32_e32 v112, 32, v162
	v_ashrrev_i32_e32 v113, 31, v112
	v_lshlrev_b64 v[114:115], 10, v[112:113]
	v_lshl_add_u64 v[114:115], v[114:115], 0, v[160:161]
	v_lshlrev_b64 v[122:123], 2, v[114:115]
	v_lshl_add_u64 v[124:125], s[16:17], 0, v[122:123]
	v_mov_b64_e32 v[126:127], s[18:19]
	v_mad_i64_i32 v[126:127], s[8:9], v112, s66, v[126:127]
	v_lshl_add_u64 v[126:127], v[160:161], 1, v[126:127]
	v_lshl_add_u64 v[122:123], s[12:13], 0, v[122:123]
	v_pk_add_f32 v[110:111], v[110:111], v[218:219]
	v_pk_add_f32 v[108:109], v[108:109], v[216:217]
	v_pk_add_f32 v[106:107], v[106:107], v[222:223]
	v_pk_add_f32 v[104:105], v[104:105], v[220:221]
	v_pk_mul_f32 v[116:117], v[94:95], v[110:111]
	v_pk_mul_f32 v[114:115], v[92:93], v[108:109]
	v_pk_mul_f32 v[118:119], v[90:91], v[106:107]
	v_pk_mul_f32 v[120:121], v[88:89], v[104:105]
	v_cvt_pk_bf16_f32 v114, v114, v115
	v_cvt_pk_bf16_f32 v115, v116, v117
	v_cvt_pk_bf16_f32 v116, v120, v121
	v_cvt_pk_bf16_f32 v117, v118, v119
	global_store_dwordx4 v[122:123], v[108:111], off
	global_store_dwordx4 v[122:123], v[104:107], off offset:16
	global_store_dwordx4 v[126:127], v[114:117], off
	v_mul_f32_e32 v109, v109, v109
	v_mul_f32_e32 v111, v111, v111
	v_mul_f32_e32 v105, v105, v105
	v_fmac_f32_e32 v109, v108, v108
	v_fmac_f32_e32 v111, v110, v110
	v_mul_f32_e32 v107, v107, v107
	v_fmac_f32_e32 v105, v104, v104
	v_add_f32_e32 v104, v109, v111
	v_fmac_f32_e32 v107, v106, v106
	v_add_f32_e32 v104, v104, v105
	v_add_f32_e32 v124, v107, v104
	v_pk_add_f32 v[102:103], v[102:103], v[226:227]
	v_pk_add_f32 v[100:101], v[100:101], v[224:225]
	v_pk_add_f32 v[96:97], v[96:97], v[228:229]
	v_mul_f32_e32 v114, v101, v101
	v_mul_f32_e32 v115, v103, v103
	v_pk_add_f32 v[98:99], v[98:99], v[230:231]
	v_mul_f32_e32 v116, v97, v97
	v_fmac_f32_e32 v114, v100, v100
	v_fmac_f32_e32 v115, v102, v102
	global_store_dwordx4 v[122:123], v[100:103], off offset:512
	global_store_dwordx4 v[122:123], v[96:99], off offset:528
	v_mul_f32_e32 v117, v99, v99
	v_pk_mul_f32 v[110:111], v[80:81], v[96:97]
	v_fmac_f32_e32 v116, v96, v96
	v_add_f32_e32 v97, v114, v115
	v_fmac_f32_e32 v117, v98, v98
	v_add_f32_e32 v97, v97, v116
	v_add_f32_e32 v97, v117, v97
	v_pk_mul_f32 v[106:107], v[84:85], v[100:101]
	v_add_f32_e32 v100, v124, v97
	ds_swizzle_b32 v101, v100 offset:swizzle(SWAP,16)
	v_pk_mul_f32 v[104:105], v[86:87], v[102:103]
	v_pk_mul_f32 v[108:109], v[82:83], v[98:99]
	v_cvt_pk_bf16_f32 v96, v106, v107
	v_cvt_pk_bf16_f32 v97, v104, v105
	v_cvt_pk_bf16_f32 v98, v110, v111
	v_cvt_pk_bf16_f32 v99, v108, v109
	global_store_dwordx4 v[126:127], v[96:99], off offset:256
	s_waitcnt lgkmcnt(0)
	s_nop 0
	v_add_f32_e32 v96, v100, v101
	v_mov_b32_e32 v97, v96
	s_nop 1
	v_permlane32_swap_b32_e32 v96, v97
	s_and_saveexec_b64 s[8:9], s[4:5]
	s_cbranch_execz .LBB0_642
	v_lshl_add_u64 v[98:99], v[112:113], 2, s[28:29]
	v_add_f32_e32 v96, v96, v97
	global_atomic_add_f32 v[98:99], v96, off
; __device__ __forceinline__ unsigned cvt_pk_bf16(float lo, float hi) { f32x2v_t v = {lo, hi}; bf16x2v_t b = __builtin_convertvector(v, bf16x2v_t); return __builtin_bit_cast(unsigned, b); }
;     __device__ __forceinline__ void operator()(PG8_ACC, const Unit& u, int wr, int wc, int fr, int fq) const {
;     ...
;         for (int ai = 0; ai < 2; ++ai)
; #pragma unroll
;             for (int m = 0; m < 4; ++m) { const int row = row0 + ai * HALF + m * 16; const size_t off = (size_t)row * ld + col0; float s = 0.f;
; #pragma unroll
;                 for (int bj = 0; bj < 2; ++bj) {
;                     const f32x4 r0 = *(const f32x4*)(res + off + bj * HALF), r1 = *(const f32x4*)(res + off + bj * HALF + 4);
;                     const f32x4 v0 = acc[ai][bj][m][0] + r0, v1 = acc[ai][bj][m][1] + r1;
;                     *(f32x4*)(out + off + bj * HALF) = v0; *(f32x4*)(out + off + bj * HALF + 4) = v1;
;                     s += (v0[0] * v0[0] + v0[1] * v0[1]) + (v0[2] * v0[2] + v0[3] * v0[3]) + (v1[0] * v1[0] + v1[1] * v1[1]) + (v1[2] * v1[2] + v1[3] * v1[3]);
;                     const f32x4 h0 = v0 * gv[bj][0], h1 = v1 * gv[bj][1];
;                     u32x4 w; w.x = cvt_pk_bf16(h0[0], h0[1]); w.y = cvt_pk_bf16(h0[2], h0[3]); w.z = cvt_pk_bf16(h1[0], h1[1]); w.w = cvt_pk_bf16(h1[2], h1[3]);
;                     *(u32x4*)(H + (size_t)row * ldh + col0 + bj * HALF) = w; }
;                 s += shx<16>(s); s = sum_halves(s);
;                 if (fq == 0) atomicAdd(SSQ + row, s); }
.LBB0_642:
	s_or_b64 exec, exec, s[8:9]
	global_load_dwordx4 v[216:219], v[248:249], off
	global_load_dwordx4 v[220:223], v[248:249], off offset:16
	global_load_dwordx4 v[224:227], v[248:249], off offset:512
	global_load_dwordx4 v[228:231], v[248:249], off offset:528
	v_lshl_add_u64 v[248:249], v[248:249], 0, s[100:101]
	v_or_b32_e32 v96, 48, v162
	v_ashrrev_i32_e32 v97, 31, v96
	v_lshlrev_b64 v[98:99], 10, v[96:97]
	v_lshl_add_u64 v[98:99], v[98:99], 0, v[160:161]
	v_lshlrev_b64 v[106:107], 2, v[98:99]
	v_lshl_add_u64 v[108:109], s[16:17], 0, v[106:107]
	v_mov_b64_e32 v[110:111], s[18:19]
	v_mad_i64_i32 v[110:111], s[8:9], v96, s66, v[110:111]
	v_lshl_add_u64 v[110:111], v[160:161], 1, v[110:111]
	v_lshl_add_u64 v[106:107], s[12:13], 0, v[106:107]
	v_pk_add_f32 v[78:79], v[78:79], v[234:235]
	v_pk_add_f32 v[76:77], v[76:77], v[232:233]
	v_pk_add_f32 v[74:75], v[74:75], v[238:239]
	v_pk_add_f32 v[72:73], v[72:73], v[236:237]
	v_pk_mul_f32 v[100:101], v[94:95], v[78:79]
	v_pk_mul_f32 v[98:99], v[92:93], v[76:77]
	v_pk_mul_f32 v[102:103], v[90:91], v[74:75]
	v_pk_mul_f32 v[104:105], v[88:89], v[72:73]
	v_cvt_pk_bf16_f32 v98, v98, v99
	v_cvt_pk_bf16_f32 v99, v100, v101
	v_cvt_pk_bf16_f32 v100, v104, v105
	v_cvt_pk_bf16_f32 v101, v102, v103
	global_store_dwordx4 v[106:107], v[76:79], off
	global_store_dwordx4 v[106:107], v[72:75], off offset:16
	global_store_dwordx4 v[110:111], v[98:101], off
	v_mul_f32_e32 v77, v77, v77
	v_mul_f32_e32 v79, v79, v79
	v_mul_f32_e32 v73, v73, v73
	v_fmac_f32_e32 v77, v76, v76
	v_fmac_f32_e32 v79, v78, v78
	v_mul_f32_e32 v75, v75, v75
	v_fmac_f32_e32 v73, v72, v72
	v_add_f32_e32 v72, v77, v79
	v_fmac_f32_e32 v75, v74, v74
	v_add_f32_e32 v72, v72, v73
	v_add_f32_e32 v108, v75, v72
	v_pk_add_f32 v[70:71], v[70:71], v[242:243]
	v_pk_add_f32 v[68:69], v[68:69], v[240:241]
	v_pk_add_f32 v[64:65], v[64:65], v[244:245]
	v_mul_f32_e32 v98, v69, v69
	v_mul_f32_e32 v99, v71, v71
	v_pk_add_f32 v[66:67], v[66:67], v[246:247]
	v_mul_f32_e32 v100, v65, v65
	v_fmac_f32_e32 v98, v68, v68
	v_fmac_f32_e32 v99, v70, v70
	global_store_dwordx4 v[106:107], v[68:71], off offset:512
	global_store_dwordx4 v[106:107], v[64:67], off offset:528
	v_mul_f32_e32 v101, v67, v67
	v_pk_mul_f32 v[78:79], v[80:81], v[64:65]
	v_fmac_f32_e32 v100, v64, v64
	v_add_f32_e32 v65, v98, v99
	v_fmac_f32_e32 v101, v66, v66
	v_add_f32_e32 v65, v65, v100
	v_add_f32_e32 v65, v101, v65
	v_pk_mul_f32 v[74:75], v[84:85], v[68:69]
	v_add_f32_e32 v68, v108, v65
	ds_swizzle_b32 v69, v68 offset:swizzle(SWAP,16)
	v_pk_mul_f32 v[72:73], v[86:87], v[70:71]
	v_pk_mul_f32 v[76:77], v[82:83], v[66:67]
	v_cvt_pk_bf16_f32 v64, v74, v75
	v_cvt_pk_bf16_f32 v65, v72, v73
	v_cvt_pk_bf16_f32 v66, v78, v79
	v_cvt_pk_bf16_f32 v67, v76, v77
	global_store_dwordx4 v[110:111], v[64:67], off offset:256
	s_waitcnt lgkmcnt(0)
	s_nop 0
	v_add_f32_e32 v64, v68, v69
	v_mov_b32_e32 v65, v64
	s_nop 1
	v_permlane32_swap_b32_e32 v64, v65
	s_and_saveexec_b64 s[8:9], s[4:5]
	s_cbranch_execz .LBB0_644
	v_lshl_add_u64 v[66:67], v[96:97], 2, s[28:29]
	v_add_f32_e32 v64, v64, v65
	global_atomic_add_f32 v[66:67], v64, off
.LBB0_644:
	s_or_b64 exec, exec, s[8:9]
	global_load_dwordx4 v[232:235], v[248:249], off
	global_load_dwordx4 v[236:239], v[248:249], off offset:16
	global_load_dwordx4 v[240:243], v[248:249], off offset:512
	global_load_dwordx4 v[244:247], v[248:249], off offset:528
	v_lshl_add_u64 v[248:249], v[248:249], 0, s[100:101]
	v_add_u32_e32 v64, 0x80, v162
	v_ashrrev_i32_e32 v65, 31, v64
	v_lshlrev_b64 v[66:67], 10, v[64:65]
	v_lshl_add_u64 v[66:67], v[66:67], 0, v[160:161]
	v_lshlrev_b64 v[74:75], 2, v[66:67]
	v_lshl_add_u64 v[76:77], s[16:17], 0, v[74:75]
	s_waitcnt vmcnt(16)
	v_mov_b64_e32 v[78:79], s[18:19]
	v_mad_i64_i32 v[78:79], s[8:9], v64, s66, v[78:79]
	v_lshl_add_u64 v[78:79], v[160:161], 1, v[78:79]
	v_lshl_add_u64 v[74:75], s[12:13], 0, v[74:75]
	v_pk_add_f32 v[62:63], v[62:63], v[186:187]
	v_pk_add_f32 v[60:61], v[60:61], v[184:185]
	v_pk_add_f32 v[58:59], v[58:59], v[190:191]
	v_pk_add_f32 v[56:57], v[56:57], v[188:189]
	v_pk_mul_f32 v[68:69], v[94:95], v[62:63]
	v_pk_mul_f32 v[66:67], v[92:93], v[60:61]
	v_pk_mul_f32 v[70:71], v[90:91], v[58:59]
	v_pk_mul_f32 v[72:73], v[88:89], v[56:57]
	v_cvt_pk_bf16_f32 v66, v66, v67
	v_cvt_pk_bf16_f32 v67, v68, v69
	v_cvt_pk_bf16_f32 v68, v72, v73
	v_cvt_pk_bf16_f32 v69, v70, v71
	global_store_dwordx4 v[74:75], v[60:63], off
	global_store_dwordx4 v[74:75], v[56:59], off offset:16
	global_store_dwordx4 v[78:79], v[66:69], off
	v_mul_f32_e32 v61, v61, v61
	v_mul_f32_e32 v63, v63, v63
	v_mul_f32_e32 v57, v57, v57
	v_fmac_f32_e32 v61, v60, v60
	v_fmac_f32_e32 v63, v62, v62
	v_mul_f32_e32 v59, v59, v59
	v_fmac_f32_e32 v57, v56, v56
	v_add_f32_e32 v56, v61, v63
	v_fmac_f32_e32 v59, v58, v58
	v_add_f32_e32 v56, v56, v57
	v_add_f32_e32 v76, v59, v56
	v_pk_add_f32 v[54:55], v[54:55], v[194:195]
	v_pk_add_f32 v[52:53], v[52:53], v[192:193]
	v_pk_add_f32 v[48:49], v[48:49], v[196:197]
	v_mul_f32_e32 v66, v53, v53
	v_mul_f32_e32 v67, v55, v55
	v_pk_add_f32 v[50:51], v[50:51], v[198:199]
	v_mul_f32_e32 v68, v49, v49
	v_fmac_f32_e32 v66, v52, v52
	v_fmac_f32_e32 v67, v54, v54
	global_store_dwordx4 v[74:75], v[52:55], off offset:512
	global_store_dwordx4 v[74:75], v[48:51], off offset:528
	v_mul_f32_e32 v69, v51, v51
	v_pk_mul_f32 v[62:63], v[80:81], v[48:49]
	v_fmac_f32_e32 v68, v48, v48
	v_add_f32_e32 v49, v66, v67
	v_fmac_f32_e32 v69, v50, v50
	v_add_f32_e32 v49, v49, v68
	v_add_f32_e32 v49, v69, v49
	v_pk_mul_f32 v[58:59], v[84:85], v[52:53]
	v_add_f32_e32 v52, v76, v49
	ds_swizzle_b32 v53, v52 offset:swizzle(SWAP,16)
	v_pk_mul_f32 v[56:57], v[86:87], v[54:55]
	v_pk_mul_f32 v[60:61], v[82:83], v[50:51]
	v_cvt_pk_bf16_f32 v48, v58, v59
	v_cvt_pk_bf16_f32 v49, v56, v57
	v_cvt_pk_bf16_f32 v50, v62, v63
	v_cvt_pk_bf16_f32 v51, v60, v61
	global_store_dwordx4 v[78:79], v[48:51], off offset:256
	s_waitcnt lgkmcnt(0)
	s_nop 0
	v_add_f32_e32 v48, v52, v53
	v_mov_b32_e32 v49, v48
	s_nop 1
	v_permlane32_swap_b32_e32 v48, v49
	s_and_saveexec_b64 s[8:9], s[4:5]
	s_cbranch_execz .LBB0_646
	v_lshl_add_u64 v[50:51], v[64:65], 2, s[28:29]
	v_add_f32_e32 v48, v48, v49
	global_atomic_add_f32 v[50:51], v48, off
; __device__ __forceinline__ unsigned cvt_pk_bf16(float lo, float hi) { f32x2v_t v = {lo, hi}; bf16x2v_t b = __builtin_convertvector(v, bf16x2v_t); return __builtin_bit_cast(unsigned, b); }
;     __device__ __forceinline__ void operator()(PG8_ACC, const Unit& u, int wr, int wc, int fr, int fq) const {
;     ...
;         for (int ai = 0; ai < 2; ++ai)
; #pragma unroll
;             for (int m = 0; m < 4; ++m) { const int row = row0 + ai * HALF + m * 16; const size_t off = (size_t)row * ld + col0; float s = 0.f;
; #pragma unroll
;                 for (int bj = 0; bj < 2; ++bj) {
;                     const f32x4 r0 = *(const f32x4*)(res + off + bj * HALF), r1 = *(const f32x4*)(res + off + bj * HALF + 4);
;                     const f32x4 v0 = acc[ai][bj][m][0] + r0, v1 = acc[ai][bj][m][1] + r1;
;                     *(f32x4*)(out + off + bj * HALF) = v0; *(f32x4*)(out + off + bj * HALF + 4) = v1;
;                     s += (v0[0] * v0[0] + v0[1] * v0[1]) + (v0[2] * v0[2] + v0[3] * v0[3]) + (v1[0] * v1[0] + v1[1] * v1[1]) + (v1[2] * v1[2] + v1[3] * v1[3]);
;                     const f32x4 h0 = v0 * gv[bj][0], h1 = v1 * gv[bj][1];
;                     u32x4 w; w.x = cvt_pk_bf16(h0[0], h0[1]); w.y = cvt_pk_bf16(h0[2], h0[3]); w.z = cvt_pk_bf16(h1[0], h1[1]); w.w = cvt_pk_bf16(h1[2], h1[3]);
;                     *(u32x4*)(H + (size_t)row * ldh + col0 + bj * HALF) = w; }
;                 s += shx<16>(s); s = sum_halves(s);
;                 if (fq == 0) atomicAdd(SSQ + row, s); }
.LBB0_646:
	s_or_b64 exec, exec, s[8:9]
	v_add_u32_e32 v48, 0x90, v162
	v_ashrrev_i32_e32 v49, 31, v48
	v_lshlrev_b64 v[50:51], 10, v[48:49]
	v_lshl_add_u64 v[50:51], v[50:51], 0, v[160:161]
	v_lshlrev_b64 v[58:59], 2, v[50:51]
	v_lshl_add_u64 v[60:61], s[16:17], 0, v[58:59]
	s_waitcnt vmcnt(16)
	v_mov_b64_e32 v[62:63], s[18:19]
	v_mad_i64_i32 v[62:63], s[8:9], v48, s66, v[62:63]
	v_lshl_add_u64 v[62:63], v[160:161], 1, v[62:63]
	v_lshl_add_u64 v[58:59], s[12:13], 0, v[58:59]
	v_pk_add_f32 v[46:47], v[46:47], v[202:203]
	v_pk_add_f32 v[44:45], v[44:45], v[200:201]
	v_pk_add_f32 v[42:43], v[42:43], v[206:207]
	v_pk_add_f32 v[40:41], v[40:41], v[204:205]
	v_pk_mul_f32 v[52:53], v[94:95], v[46:47]
	v_pk_mul_f32 v[50:51], v[92:93], v[44:45]
	v_pk_mul_f32 v[54:55], v[90:91], v[42:43]
	v_pk_mul_f32 v[56:57], v[88:89], v[40:41]
	v_cvt_pk_bf16_f32 v50, v50, v51
	v_cvt_pk_bf16_f32 v51, v52, v53
	v_cvt_pk_bf16_f32 v52, v56, v57
	v_cvt_pk_bf16_f32 v53, v54, v55
	global_store_dwordx4 v[58:59], v[44:47], off
	global_store_dwordx4 v[58:59], v[40:43], off offset:16
	global_store_dwordx4 v[62:63], v[50:53], off
	v_mul_f32_e32 v45, v45, v45
	v_mul_f32_e32 v47, v47, v47
	v_mul_f32_e32 v41, v41, v41
	v_fmac_f32_e32 v45, v44, v44
	v_fmac_f32_e32 v47, v46, v46
	v_mul_f32_e32 v43, v43, v43
	v_fmac_f32_e32 v41, v40, v40
	v_add_f32_e32 v40, v45, v47
	v_fmac_f32_e32 v43, v42, v42
	v_add_f32_e32 v40, v40, v41
	v_add_f32_e32 v60, v43, v40
	v_pk_add_f32 v[38:39], v[38:39], v[210:211]
	v_pk_add_f32 v[36:37], v[36:37], v[208:209]
	v_pk_add_f32 v[32:33], v[32:33], v[212:213]
	v_mul_f32_e32 v50, v37, v37
	v_mul_f32_e32 v51, v39, v39
	v_pk_add_f32 v[34:35], v[34:35], v[214:215]
	v_mul_f32_e32 v52, v33, v33
	v_fmac_f32_e32 v50, v36, v36
	v_fmac_f32_e32 v51, v38, v38
	global_store_dwordx4 v[58:59], v[36:39], off offset:512
	global_store_dwordx4 v[58:59], v[32:35], off offset:528
	v_mul_f32_e32 v53, v35, v35
	v_pk_mul_f32 v[46:47], v[80:81], v[32:33]
	v_fmac_f32_e32 v52, v32, v32
	v_add_f32_e32 v33, v50, v51
	v_fmac_f32_e32 v53, v34, v34
	v_add_f32_e32 v33, v33, v52
	v_add_f32_e32 v33, v53, v33
	v_pk_mul_f32 v[42:43], v[84:85], v[36:37]
	v_add_f32_e32 v36, v60, v33
	ds_swizzle_b32 v37, v36 offset:swizzle(SWAP,16)
	v_pk_mul_f32 v[40:41], v[86:87], v[38:39]
	v_pk_mul_f32 v[44:45], v[82:83], v[34:35]
	v_cvt_pk_bf16_f32 v32, v42, v43
	v_cvt_pk_bf16_f32 v33, v40, v41
	v_cvt_pk_bf16_f32 v34, v46, v47
	v_cvt_pk_bf16_f32 v35, v44, v45
	global_store_dwordx4 v[62:63], v[32:35], off offset:256
	s_waitcnt lgkmcnt(0)
	s_nop 0
	v_add_f32_e32 v32, v36, v37
	v_mov_b32_e32 v33, v32
	s_nop 1
	v_permlane32_swap_b32_e32 v32, v33
	s_and_saveexec_b64 s[8:9], s[4:5]
	s_cbranch_execz .LBB0_648
	v_lshl_add_u64 v[34:35], v[48:49], 2, s[28:29]
	v_add_f32_e32 v32, v32, v33
	global_atomic_add_f32 v[34:35], v32, off
; __device__ __forceinline__ unsigned cvt_pk_bf16(float lo, float hi) { f32x2v_t v = {lo, hi}; bf16x2v_t b = __builtin_convertvector(v, bf16x2v_t); return __builtin_bit_cast(unsigned, b); }
;     __device__ __forceinline__ void operator()(PG8_ACC, const Unit& u, int wr, int wc, int fr, int fq) const {
;     ...
;         for (int ai = 0; ai < 2; ++ai)
; #pragma unroll
;             for (int m = 0; m < 4; ++m) { const int row = row0 + ai * HALF + m * 16; const size_t off = (size_t)row * ld + col0; float s = 0.f;
; #pragma unroll
;                 for (int bj = 0; bj < 2; ++bj) {
;                     const f32x4 r0 = *(const f32x4*)(res + off + bj * HALF), r1 = *(const f32x4*)(res + off + bj * HALF + 4);
;                     const f32x4 v0 = acc[ai][bj][m][0] + r0, v1 = acc[ai][bj][m][1] + r1;
;                     *(f32x4*)(out + off + bj * HALF) = v0; *(f32x4*)(out + off + bj * HALF + 4) = v1;
;                     s += (v0[0] * v0[0] + v0[1] * v0[1]) + (v0[2] * v0[2] + v0[3] * v0[3]) + (v1[0] * v1[0] + v1[1] * v1[1]) + (v1[2] * v1[2] + v1[3] * v1[3]);
;                     const f32x4 h0 = v0 * gv[bj][0], h1 = v1 * gv[bj][1];
;                     u32x4 w; w.x = cvt_pk_bf16(h0[0], h0[1]); w.y = cvt_pk_bf16(h0[2], h0[3]); w.z = cvt_pk_bf16(h1[0], h1[1]); w.w = cvt_pk_bf16(h1[2], h1[3]);
;                     *(u32x4*)(H + (size_t)row * ldh + col0 + bj * HALF) = w; }
;                 s += shx<16>(s); s = sum_halves(s);
;                 if (fq == 0) atomicAdd(SSQ + row, s); }
.LBB0_648:
	s_or_b64 exec, exec, s[8:9]
	v_add_u32_e32 v32, 0xa0, v162
	v_ashrrev_i32_e32 v33, 31, v32
	v_lshlrev_b64 v[34:35], 10, v[32:33]
	v_lshl_add_u64 v[34:35], v[34:35], 0, v[160:161]
	v_lshlrev_b64 v[42:43], 2, v[34:35]
	v_lshl_add_u64 v[44:45], s[16:17], 0, v[42:43]
	s_waitcnt vmcnt(16)
	v_mov_b64_e32 v[46:47], s[18:19]
	v_mad_i64_i32 v[46:47], s[8:9], v32, s66, v[46:47]
	v_lshl_add_u64 v[46:47], v[160:161], 1, v[46:47]
	v_lshl_add_u64 v[42:43], s[12:13], 0, v[42:43]
	v_pk_add_f32 v[30:31], v[30:31], v[218:219]
	v_pk_add_f32 v[28:29], v[28:29], v[216:217]
	v_pk_add_f32 v[26:27], v[26:27], v[222:223]
	v_pk_add_f32 v[24:25], v[24:25], v[220:221]
	v_pk_mul_f32 v[36:37], v[94:95], v[30:31]
	v_pk_mul_f32 v[34:35], v[92:93], v[28:29]
	v_pk_mul_f32 v[38:39], v[90:91], v[26:27]
	v_pk_mul_f32 v[40:41], v[88:89], v[24:25]
	v_cvt_pk_bf16_f32 v34, v34, v35
	v_cvt_pk_bf16_f32 v35, v36, v37
	v_cvt_pk_bf16_f32 v36, v40, v41
	v_cvt_pk_bf16_f32 v37, v38, v39
	global_store_dwordx4 v[42:43], v[28:31], off
	global_store_dwordx4 v[42:43], v[24:27], off offset:16
	global_store_dwordx4 v[46:47], v[34:37], off
	v_mul_f32_e32 v29, v29, v29
	v_mul_f32_e32 v31, v31, v31
	v_mul_f32_e32 v25, v25, v25
	v_fmac_f32_e32 v29, v28, v28
	v_fmac_f32_e32 v31, v30, v30
	v_mul_f32_e32 v27, v27, v27
	v_fmac_f32_e32 v25, v24, v24
	v_add_f32_e32 v24, v29, v31
	v_fmac_f32_e32 v27, v26, v26
	v_add_f32_e32 v24, v24, v25
	v_add_f32_e32 v44, v27, v24
	v_pk_add_f32 v[22:23], v[22:23], v[226:227]
	v_pk_add_f32 v[20:21], v[20:21], v[224:225]
	v_pk_add_f32 v[16:17], v[16:17], v[228:229]
	v_mul_f32_e32 v34, v21, v21
	v_mul_f32_e32 v35, v23, v23
	v_pk_add_f32 v[18:19], v[18:19], v[230:231]
	v_mul_f32_e32 v36, v17, v17
	v_fmac_f32_e32 v34, v20, v20
	v_fmac_f32_e32 v35, v22, v22
	global_store_dwordx4 v[42:43], v[20:23], off offset:512
	global_store_dwordx4 v[42:43], v[16:19], off offset:528
	v_mul_f32_e32 v37, v19, v19
	v_pk_mul_f32 v[30:31], v[80:81], v[16:17]
	v_fmac_f32_e32 v36, v16, v16
	v_add_f32_e32 v17, v34, v35
	v_fmac_f32_e32 v37, v18, v18
	v_add_f32_e32 v17, v17, v36
	v_add_f32_e32 v17, v37, v17
	v_pk_mul_f32 v[26:27], v[84:85], v[20:21]
	v_add_f32_e32 v20, v44, v17
	ds_swizzle_b32 v21, v20 offset:swizzle(SWAP,16)
	v_pk_mul_f32 v[24:25], v[86:87], v[22:23]
	v_pk_mul_f32 v[28:29], v[82:83], v[18:19]
	v_cvt_pk_bf16_f32 v16, v26, v27
	v_cvt_pk_bf16_f32 v17, v24, v25
	v_cvt_pk_bf16_f32 v18, v30, v31
	v_cvt_pk_bf16_f32 v19, v28, v29
	global_store_dwordx4 v[46:47], v[16:19], off offset:256
	s_waitcnt lgkmcnt(0)
	s_nop 0
	v_add_f32_e32 v16, v20, v21
	v_mov_b32_e32 v17, v16
	s_nop 1
	v_permlane32_swap_b32_e32 v16, v17
	s_and_saveexec_b64 s[8:9], s[4:5]
	s_cbranch_execz .LBB0_650
	v_lshl_add_u64 v[18:19], v[32:33], 2, s[28:29]
	v_add_f32_e32 v16, v16, v17
	global_atomic_add_f32 v[18:19], v16, off
.LBB0_650:
	s_or_b64 exec, exec, s[8:9]
	v_add_u32_e32 v16, 0xb0, v162
	v_ashrrev_i32_e32 v17, 31, v16
	v_lshlrev_b64 v[18:19], 10, v[16:17]
	v_lshl_add_u64 v[18:19], v[18:19], 0, v[160:161]
	v_lshlrev_b64 v[26:27], 2, v[18:19]
	v_lshl_add_u64 v[28:29], s[16:17], 0, v[26:27]
	s_waitcnt vmcnt(16)
	v_mov_b64_e32 v[30:31], s[18:19]
	v_mad_i64_i32 v[30:31], s[8:9], v16, s66, v[30:31]
	v_lshl_add_u64 v[30:31], v[160:161], 1, v[30:31]
	v_lshl_add_u64 v[26:27], s[12:13], 0, v[26:27]
	v_pk_add_f32 v[14:15], v[14:15], v[234:235]
	v_pk_add_f32 v[12:13], v[12:13], v[232:233]
	v_pk_add_f32 v[10:11], v[10:11], v[238:239]
	v_pk_add_f32 v[8:9], v[8:9], v[236:237]
	v_pk_mul_f32 v[20:21], v[94:95], v[14:15]
	v_pk_mul_f32 v[18:19], v[92:93], v[12:13]
	v_pk_mul_f32 v[22:23], v[90:91], v[10:11]
	v_pk_mul_f32 v[24:25], v[88:89], v[8:9]
	v_cvt_pk_bf16_f32 v18, v18, v19
	v_cvt_pk_bf16_f32 v19, v20, v21
	v_cvt_pk_bf16_f32 v20, v24, v25
	v_cvt_pk_bf16_f32 v21, v22, v23
	global_store_dwordx4 v[26:27], v[12:15], off
	global_store_dwordx4 v[26:27], v[8:11], off offset:16
	global_store_dwordx4 v[30:31], v[18:21], off
	v_mul_f32_e32 v13, v13, v13
	v_mul_f32_e32 v15, v15, v15
	v_mul_f32_e32 v9, v9, v9
	v_fmac_f32_e32 v13, v12, v12
	v_fmac_f32_e32 v15, v14, v14
	v_mul_f32_e32 v11, v11, v11
	v_fmac_f32_e32 v9, v8, v8
	v_add_f32_e32 v8, v13, v15
	v_fmac_f32_e32 v11, v10, v10
	v_add_f32_e32 v8, v8, v9
	v_add_f32_e32 v28, v11, v8
	v_pk_add_f32 v[6:7], v[6:7], v[242:243]
	v_pk_add_f32 v[4:5], v[4:5], v[240:241]
	v_pk_add_f32 v[0:1], v[0:1], v[244:245]
	v_mul_f32_e32 v18, v5, v5
	v_mul_f32_e32 v19, v7, v7
	v_pk_add_f32 v[2:3], v[2:3], v[246:247]
	v_mul_f32_e32 v20, v1, v1
	v_fmac_f32_e32 v18, v4, v4
	v_fmac_f32_e32 v19, v6, v6
	global_store_dwordx4 v[26:27], v[4:7], off offset:512
	global_store_dwordx4 v[26:27], v[0:3], off offset:528
	v_mul_f32_e32 v21, v3, v3
	v_pk_mul_f32 v[14:15], v[80:81], v[0:1]
	v_fmac_f32_e32 v20, v0, v0
	v_add_f32_e32 v1, v18, v19
	v_fmac_f32_e32 v21, v2, v2
	v_add_f32_e32 v1, v1, v20
	v_add_f32_e32 v1, v21, v1
	v_pk_mul_f32 v[10:11], v[84:85], v[4:5]
	v_add_f32_e32 v4, v28, v1
	ds_swizzle_b32 v5, v4 offset:swizzle(SWAP,16)
	v_pk_mul_f32 v[8:9], v[86:87], v[6:7]
	v_pk_mul_f32 v[12:13], v[82:83], v[2:3]
	v_cvt_pk_bf16_f32 v0, v10, v11
	v_cvt_pk_bf16_f32 v1, v8, v9
	v_cvt_pk_bf16_f32 v2, v14, v15
	v_cvt_pk_bf16_f32 v3, v12, v13
	global_store_dwordx4 v[30:31], v[0:3], off offset:256
	s_waitcnt lgkmcnt(0)
	s_nop 0
	v_add_f32_e32 v0, v4, v5
	v_mov_b32_e32 v1, v0
	s_nop 1
	v_permlane32_swap_b32_e32 v0, v1
	s_and_saveexec_b64 s[8:9], s[4:5]
	s_cbranch_execz .LBB0_652
	v_lshl_add_u64 v[2:3], v[16:17], 2, s[28:29]
	v_add_f32_e32 v0, v0, v1
	global_atomic_add_f32 v[2:3], v0, off
